# prep: q/k/v map weight fragments and GLA row loads fetched together; out: Q-state and Q-K chains fetch all k-steps up front (counted waits)
# speedup vs baseline: 1.0467x; 1.0086x over previous
; DI int crow(int i, int hh) { return (i & 3) + 8 * (i >> 2) + 4 * hh; }
; #define MFMA32(a, b, c) __builtin_amdgcn_mfma_f32_32x32x16_bf16((a), (b), (c), 0, 0, 0)
; template <int BR> DI void out_item(PARAMS P, int l, int cid, int h, LAS unsigned char* lds, int wave, int lane) {
;     ...
;     f32x16 o;
; #pragma unroll
;     for (int i = 0; i < 16; ++i) o[i] = 0.f;
; #pragma unroll
;     for (int ks = 0; ks < NKS; ++ks) {
;         const bf16x8 a = *(const bf16x8*)(Q + (size_t)(32 * tt + r) * QW + 16 * ks + 8 * hh);
;         typedef short s16x4_o __attribute__((ext_vector_type(4)));
;         const bf16_t* stp = ST + (size_t)((((ks >> 1) * 4 + 2 * (ks & 1) + hh) * 2) * 128 + 32 * vt + r) * 4;
;         const s16x4_o b0_ = *(const s16x4_o*)stp, b1_ = *(const s16x4_o*)(stp + 512);
;         const bf16x8 b = __builtin_shufflevector(b0_, b1_, 0, 1, 2, 3, 4, 5, 6, 7);
;         o = MFMA32(a, b, o);
;     }
;     if (BR == 1) {
; #pragma unroll
;         for (int i = 0; i < 16; ++i) o[i] *= __expf(mp - fmaxf(mp, Gl[32 * tt + crow(i, hh)]));
;     }
;     if (wave < 4) {
;         const int ts = wave >> 1, ss = wave & 1; f32x16 p;
; #pragma unroll
;         for (int i = 0; i < 16; ++i) p[i] = 0.f;
;         if (ss <= ts) {
; #pragma unroll
;             for (int ks = 0; ks < NKS; ++ks) {
;                 const bf16x8 a = *(const bf16x8*)(Q + (size_t)(32 * ts + r) * QW + 16 * ks + 8 * hh), b = *(const bf16x8*)(K + (size_t)(32 * ss + r) * QW + 16 * ks + 8 * hh);
;                 p = MFMA32(a, b, p);
;             }
;         }
.LBB0_470:
	s_or_b64 exec, exec, s[6:7]
	s_lshl_b64 s[52:53], s[56:57], 9
	s_lshl_b64 s[6:7], s[56:57], 10
	v_readlane_b32 s12, v254, 26
	s_add_u32 s6, s12, s6
	v_readlane_b32 s12, v254, 33
	s_addc_u32 s7, s12, s7
	s_lshl_b32 s48, s3, 7
	s_lshl_b32 s12, s3, 8
	s_add_u32 s6, s6, s12
	s_addc_u32 s7, s7, 0
	v_lshl_add_u64 v[0:1], s[6:7], 0, v[50:51]
	v_lshlrev_b32_e32 v32, 1, v52
	v_lshl_add_u64 v[26:27], v[0:1], 0, v[32:33]
	s_waitcnt vmcnt(0) lgkmcnt(0)
	s_barrier
	global_load_dwordx4 v[0:3], v[26:27], off
	s_lshl_b64 s[20:21], s[8:9], 15
	v_lshl_add_u64 v[16:17], v[56:57], 0, s[20:21]
	global_load_dwordx2 v[4:5], v[16:17], off
	global_load_dwordx2 v[6:7], v[16:17], off offset:1024
	global_load_dwordx4 v[18:21], v[26:27], off offset:32
	v_add_co_u32_e32 v28, vcc, 0x2000, v16
	s_nop 1
	v_addc_co_u32_e32 v29, vcc, 0, v17, vcc
	v_add_co_u32_e32 v164, vcc, 0x4000, v16
	s_nop 1
	v_addc_co_u32_e32 v165, vcc, 0, v17, vcc
	v_add_co_u32_e32 v166, vcc, 0x6000, v16
	s_nop 1
	v_addc_co_u32_e32 v167, vcc, 0, v17, vcc
	v_add_co_u32_e32 v168, vcc, 0x7000, v16
	s_nop 1
	v_addc_co_u32_e32 v169, vcc, 0, v17, vcc
	global_load_dwordx2 v[22:23], v[28:29], off offset:-4096
	global_load_dwordx2 v[24:25], v[28:29], off offset:-3072
	global_load_dwordx4 v[112:115], v[26:27], off offset:64
	global_load_dwordx2 v[116:117], v[28:29], off
	global_load_dwordx2 v[118:119], v[28:29], off offset:1024
	global_load_dwordx4 v[120:123], v[26:27], off offset:96
	global_load_dwordx2 v[124:125], v[164:165], off offset:-4096
	global_load_dwordx2 v[126:127], v[164:165], off offset:-3072
	global_load_dwordx4 v[128:131], v[26:27], off offset:128
	global_load_dwordx2 v[132:133], v[164:165], off
	global_load_dwordx2 v[134:135], v[164:165], off offset:1024
	global_load_dwordx4 v[136:139], v[26:27], off offset:160
	global_load_dwordx2 v[140:141], v[166:167], off offset:-4096
	global_load_dwordx2 v[142:143], v[166:167], off offset:-3072
	global_load_dwordx4 v[148:151], v[26:27], off offset:192
	global_load_dwordx2 v[152:153], v[168:169], off offset:-4096
	global_load_dwordx2 v[154:155], v[168:169], off offset:-3072
	global_load_dwordx4 v[156:159], v[26:27], off offset:224
	global_load_dwordx2 v[160:161], v[168:169], off
	global_load_dwordx2 v[162:163], v[168:169], off offset:1024
	v_readlane_b32 s12, v254, 38
	s_nop 3
	v_add_u32_e32 v16, s12, v53
	ds_read_b128 v[46:49], v16 offset:43264
	ds_read_b128 v[42:45], v16 offset:43296
	ds_read_b128 v[38:41], v16 offset:43328
	ds_read_b128 v[34:37], v16 offset:43360
	s_andn2_b64 vcc, exec, s[40:41]
	s_waitcnt vmcnt(21)
	v_mfma_f32_32x32x16_bf16 v[0:15], v[0:3], v[4:7], 0
	s_waitcnt vmcnt(18)
	v_mfma_f32_32x32x16_bf16 v[0:15], v[18:21], v[22:25], v[0:15]
	s_waitcnt vmcnt(15)
	v_mfma_f32_32x32x16_bf16 v[0:15], v[112:115], v[116:119], v[0:15]
	s_waitcnt vmcnt(12)
	v_mfma_f32_32x32x16_bf16 v[0:15], v[120:123], v[124:127], v[0:15]
	s_waitcnt vmcnt(9)
	v_mfma_f32_32x32x16_bf16 v[0:15], v[128:131], v[132:135], v[0:15]
	s_waitcnt vmcnt(6)
	v_mfma_f32_32x32x16_bf16 v[0:15], v[136:139], v[140:143], v[0:15]
	s_waitcnt vmcnt(3)
	v_mfma_f32_32x32x16_bf16 v[0:15], v[148:151], v[152:155], v[0:15]
	s_waitcnt vmcnt(0)
	v_mfma_f32_32x32x16_bf16 v[0:15], v[156:159], v[160:163], v[0:15]
	s_cbranch_vccnz .LBB0_506
	v_mov_b32_e32 v81, 0
	s_andn2_b64 vcc, exec, s[44:45]
	v_mov_b32_e32 v16, 0
	v_mov_b32_e32 v17, 0
	v_mov_b32_e32 v18, 0
	v_mov_b32_e32 v19, 0
	v_mov_b32_e32 v20, 0
	v_mov_b32_e32 v21, 0
	v_mov_b32_e32 v22, 0
	v_mov_b32_e32 v23, 0
	v_mov_b32_e32 v24, 0
	v_mov_b32_e32 v25, 0
	v_mov_b32_e32 v26, 0
	v_mov_b32_e32 v27, 0
	v_mov_b32_e32 v28, 0
	v_mov_b32_e32 v29, 0
	v_mov_b32_e32 v30, 0
	v_mov_b32_e32 v31, 0
	s_cbranch_vccnz .LBB0_473
	s_lshl_b64 s[20:21], s[52:53], 1
	v_readlane_b32 s12, v254, 40
	s_add_u32 s12, s12, s20
	v_readlane_b32 s20, v254, 41
	s_addc_u32 s21, s20, s21
	s_lshl_b32 s20, s48, 1
	s_add_u32 s20, s12, s20
	s_addc_u32 s21, s21, 0
	v_lshl_add_u64 v[16:17], s[6:7], 0, v[58:59]
	v_mov_b32_e32 v71, v33
	v_lshl_add_u64 v[90:91], v[16:17], 0, v[32:33]
	v_lshl_add_u64 v[16:17], s[20:21], 0, v[70:71]
	v_lshl_add_u64 v[92:93], v[16:17], 0, v[32:33]
	global_load_dwordx4 v[16:19], v[90:91], off
	global_load_dwordx4 v[20:23], v[92:93], off
	global_load_dwordx4 v[82:85], v[90:91], off offset:32
	global_load_dwordx4 v[86:89], v[92:93], off offset:32
	global_load_dwordx4 v[112:115], v[90:91], off offset:64
	global_load_dwordx4 v[116:119], v[92:93], off offset:64
	global_load_dwordx4 v[120:123], v[90:91], off offset:96
	global_load_dwordx4 v[124:127], v[92:93], off offset:96
	global_load_dwordx4 v[128:131], v[90:91], off offset:128
	global_load_dwordx4 v[132:135], v[92:93], off offset:128
	global_load_dwordx4 v[136:139], v[90:91], off offset:160
	global_load_dwordx4 v[140:143], v[92:93], off offset:160
	global_load_dwordx4 v[148:151], v[90:91], off offset:192
	global_load_dwordx4 v[152:155], v[92:93], off offset:192
	global_load_dwordx4 v[156:159], v[90:91], off offset:224
	global_load_dwordx4 v[160:163], v[92:93], off offset:224
	s_waitcnt vmcnt(14)
	v_mfma_f32_32x32x16_bf16 v[16:31], v[16:19], v[20:23], 0
	s_waitcnt vmcnt(12)
	v_mfma_f32_32x32x16_bf16 v[16:31], v[82:85], v[86:89], v[16:31]
	s_waitcnt vmcnt(10)
	v_mfma_f32_32x32x16_bf16 v[16:31], v[112:115], v[116:119], v[16:31]
	s_waitcnt vmcnt(8)
	v_mfma_f32_32x32x16_bf16 v[16:31], v[120:123], v[124:127], v[16:31]
	s_waitcnt vmcnt(6)
	v_mfma_f32_32x32x16_bf16 v[16:31], v[128:131], v[132:135], v[16:31]
	s_waitcnt vmcnt(4)
	v_mfma_f32_32x32x16_bf16 v[16:31], v[136:139], v[140:143], v[16:31]
	s_waitcnt vmcnt(2)
	v_mfma_f32_32x32x16_bf16 v[16:31], v[148:151], v[152:155], v[16:31]
	s_waitcnt vmcnt(0)
	v_mfma_f32_32x32x16_bf16 v[16:31], v[156:159], v[160:163], v[16:31]

; DI int crow(int i, int hh) { return (i & 3) + 8 * (i >> 2) + 4 * hh; }
; #define MFMA32(a, b, c) __builtin_amdgcn_mfma_f32_32x32x16_bf16((a), (b), (c), 0, 0, 0)
; template <int BR> DI void out_item(PARAMS P, int l, int cid, int h, LAS unsigned char* lds, int wave, int lane) {
;     ...
;     for (int ks = 0; ks < NKS; ++ks) {
;         const bf16x8 a = *(const bf16x8*)(Q + (size_t)(32 * tt + r) * QW + 16 * ks + 8 * hh);
;         typedef short s16x4_o __attribute__((ext_vector_type(4)));
;         const bf16_t* stp = ST + (size_t)((((ks >> 1) * 4 + 2 * (ks & 1) + hh) * 2) * 128 + 32 * vt + r) * 4;
;         const s16x4_o b0_ = *(const s16x4_o*)stp, b1_ = *(const s16x4_o*)(stp + 512);
;         const bf16x8 b = __builtin_shufflevector(b0_, b1_, 0, 1, 2, 3, 4, 5, 6, 7);
;         o = MFMA32(a, b, o);
;     }
;     if (BR == 1) {
; #pragma unroll
;         for (int i = 0; i < 16; ++i) o[i] *= __expf(mp - fmaxf(mp, Gl[32 * tt + crow(i, hh)]));
;     }
;     if (wave < 4) {
;         const int ts = wave >> 1, ss = wave & 1; f32x16 p;
; #pragma unroll
;         for (int i = 0; i < 16; ++i) p[i] = 0.f;
;         if (ss <= ts) {
; #pragma unroll
;             for (int ks = 0; ks < NKS; ++ks) {
;                 const bf16x8 a = *(const bf16x8*)(Q + (size_t)(32 * ts + r) * QW + 16 * ks + 8 * hh), b = *(const bf16x8*)(K + (size_t)(32 * ss + r) * QW + 16 * ks + 8 * hh);
;                 p = MFMA32(a, b, p);
;             }
;         }
.LBB0_510:
	v_cndmask_b32_e64 v0, 0, 1, s[40:41]
	s_andn2_b64 vcc, exec, s[6:7]
	v_lshlrev_b32_e32 v32, 1, v52
	v_cmp_ne_u32_e64 s[8:9], 1, v0
	s_cbranch_vccnz .LBB0_516
	s_lshl_b32 s6, s68, 2
	s_or_b32 s6, s6, s3
	s_ashr_i32 s7, s6, 31
	s_lshl_b64 s[16:17], s[6:7], 14
	s_lshl_b64 s[6:7], s[56:57], 9
	s_add_u32 s6, s60, s6
	s_addc_u32 s7, s61, s7
	s_lshl_b32 s12, s3, 7
	s_add_u32 s6, s6, s12
	s_addc_u32 s7, s7, 0
	v_lshl_add_u64 v[0:1], s[6:7], 0, v[64:65]
	v_mov_b32_e32 v34, v228
	v_lshl_add_u64 v[24:25], v[0:1], 0, v[32:33]
	global_load_dwordx4 v[0:3], v[24:25], off
	v_lshl_add_u64 v[26:27], v[68:69], 0, s[16:17]
	global_load_dwordx2 v[4:5], v[26:27], off
	global_load_dwordx2 v[6:7], v[26:27], off offset:1024
	global_load_dwordx4 v[16:19], v[24:25], off offset:32
	v_add_co_u32_e32 v28, vcc, 0x2000, v26
	s_nop 1
	v_addc_co_u32_e32 v29, vcc, 0, v27, vcc
	v_add_co_u32_e32 v126, vcc, 0x3000, v26
	s_nop 1
	v_addc_co_u32_e32 v127, vcc, 0, v27, vcc
	global_load_dwordx2 v[20:21], v[28:29], off offset:-4096
	global_load_dwordx2 v[22:23], v[28:29], off offset:-3072
	global_load_dwordx4 v[112:115], v[24:25], off offset:64
	global_load_dwordx2 v[116:117], v[126:127], off offset:-4096
	global_load_dwordx2 v[118:119], v[126:127], off offset:-3072
	global_load_dwordx4 v[120:123], v[24:25], off offset:96
	global_load_dwordx2 v[124:125], v[126:127], off
	global_load_dwordx2 v[126:127], v[126:127], off offset:1024
	s_waitcnt vmcnt(9)
	v_mfma_f32_32x32x16_bf16 v[0:15], v[0:3], v[4:7], 0
	s_waitcnt vmcnt(6)
	v_mfma_f32_32x32x16_bf16 v[0:15], v[16:19], v[20:23], v[0:15]
	s_waitcnt vmcnt(3)
	v_mfma_f32_32x32x16_bf16 v[0:15], v[112:115], v[116:119], v[0:15]
	s_waitcnt vmcnt(0)
	v_mfma_f32_32x32x16_bf16 v[0:15], v[120:123], v[124:127], v[0:15]
	s_and_b64 vcc, exec, s[8:9]
	s_cbranch_vccnz .LBB0_515
	v_mov_b32_e32 v16, 0
	s_andn2_b64 vcc, exec, s[44:45]
	v_mov_b32_e32 v17, 0
	v_mov_b32_e32 v18, 0
	v_mov_b32_e32 v19, 0
	v_mov_b32_e32 v20, 0
	v_mov_b32_e32 v21, 0
	v_mov_b32_e32 v22, 0
	v_mov_b32_e32 v23, 0
	v_mov_b32_e32 v24, 0
	v_mov_b32_e32 v25, 0
	v_mov_b32_e32 v26, 0
	v_mov_b32_e32 v27, 0
	v_mov_b32_e32 v28, 0
	v_mov_b32_e32 v29, 0
	v_mov_b32_e32 v30, 0
	v_mov_b32_e32 v31, 0
	s_cbranch_vccnz .LBB0_514
	s_lshl_b64 s[16:17], s[56:57], 8
	s_lshl_b32 s12, s3, 6
	s_lshl_b64 s[16:17], s[16:17], 1
	v_readlane_b32 s20, v252, 2
	s_add_u32 s16, s20, s16
	v_readlane_b32 s20, v252, 3
	s_addc_u32 s17, s20, s17
	s_lshl_b32 s12, s12, 1
	s_add_u32 s16, s16, s12
	v_lshl_add_u64 v[16:17], s[6:7], 0, v[66:67]
	s_addc_u32 s17, s17, 0
	v_lshl_add_u64 v[44:45], v[16:17], 0, v[32:33]
	v_lshlrev_b32_e32 v16, 1, v62
	v_mov_b32_e32 v17, v33
	v_lshl_add_u64 v[16:17], s[16:17], 0, v[16:17]
	v_lshl_add_u64 v[46:47], v[16:17], 0, v[32:33]
	global_load_dwordx4 v[16:19], v[44:45], off
	global_load_dwordx4 v[20:23], v[46:47], off
	global_load_dwordx4 v[36:39], v[44:45], off offset:32
	global_load_dwordx4 v[40:43], v[46:47], off offset:32
	global_load_dwordx4 v[112:115], v[44:45], off offset:64
	global_load_dwordx4 v[116:119], v[46:47], off offset:64
	global_load_dwordx4 v[120:123], v[44:45], off offset:96
	global_load_dwordx4 v[124:127], v[46:47], off offset:96
	s_waitcnt vmcnt(6)
	v_mfma_f32_32x32x16_bf16 v[16:31], v[16:19], v[20:23], 0
	s_waitcnt vmcnt(4)
	v_mfma_f32_32x32x16_bf16 v[16:31], v[36:39], v[40:43], v[16:31]
	s_waitcnt vmcnt(2)
	v_mfma_f32_32x32x16_bf16 v[16:31], v[112:115], v[116:119], v[16:31]
	s_waitcnt vmcnt(0)
	v_mfma_f32_32x32x16_bf16 v[16:31], v[120:123], v[124:127], v[16:31]

; DI int crow(int i, int hh) { return (i & 3) + 8 * (i >> 2) + 4 * hh; }
; #define MFMA32(a, b, c) __builtin_amdgcn_mfma_f32_32x32x16_bf16((a), (b), (c), 0, 0, 0)
; template <int BR> DI void out_item(PARAMS P, int l, int cid, int h, LAS unsigned char* lds, int wave, int lane) {
;     ...
;     for (int ks = 0; ks < NKS; ++ks) {
;         const bf16x8 a = *(const bf16x8*)(Q + (size_t)(32 * tt + r) * QW + 16 * ks + 8 * hh);
;         typedef short s16x4_o __attribute__((ext_vector_type(4)));
;         const bf16_t* stp = ST + (size_t)((((ks >> 1) * 4 + 2 * (ks & 1) + hh) * 2) * 128 + 32 * vt + r) * 4;
;         const s16x4_o b0_ = *(const s16x4_o*)stp, b1_ = *(const s16x4_o*)(stp + 512);
;         const bf16x8 b = __builtin_shufflevector(b0_, b1_, 0, 1, 2, 3, 4, 5, 6, 7);
;         o = MFMA32(a, b, o);
;     }
;     if (BR == 1) {
; #pragma unroll
;         for (int i = 0; i < 16; ++i) o[i] *= __expf(mp - fmaxf(mp, Gl[32 * tt + crow(i, hh)]));
;     }
;     if (wave < 4) {
;         const int ts = wave >> 1, ss = wave & 1; f32x16 p;
; #pragma unroll
;         for (int i = 0; i < 16; ++i) p[i] = 0.f;
;         if (ss <= ts) {
; #pragma unroll
;             for (int ks = 0; ks < NKS; ++ks) {
;                 const bf16x8 a = *(const bf16x8*)(Q + (size_t)(32 * ts + r) * QW + 16 * ks + 8 * hh), b = *(const bf16x8*)(K + (size_t)(32 * ss + r) * QW + 16 * ks + 8 * hh);
;                 p = MFMA32(a, b, p);
;             }
;         }
.LBB0_516:
	s_and_b64 vcc, exec, s[16:17]
	s_cbranch_vccz .LBB0_465
	s_lshl_b32 s6, s68, 2
	s_or_b32 s6, s6, s3
	s_ashr_i32 s7, s6, 31
	s_lshl_b64 s[16:17], s[6:7], 14
	s_lshl_b64 s[6:7], s[56:57], 9
	s_add_u32 s6, s69, s6
	s_addc_u32 s7, s72, s7
	s_lshl_b32 s12, s3, 7
	s_add_u32 s6, s6, s12
	s_addc_u32 s7, s7, 0
	v_lshl_add_u64 v[0:1], s[6:7], 0, v[64:65]
	v_mov_b32_e32 v34, v228
	v_lshl_add_u64 v[24:25], v[0:1], 0, v[32:33]
	global_load_dwordx4 v[0:3], v[24:25], off
	v_lshl_add_u64 v[26:27], v[54:55], 0, s[16:17]
	global_load_dwordx2 v[4:5], v[26:27], off
	global_load_dwordx2 v[6:7], v[26:27], off offset:1024
	global_load_dwordx4 v[16:19], v[24:25], off offset:32
	v_add_co_u32_e32 v28, vcc, 0x2000, v26
	s_nop 1
	v_addc_co_u32_e32 v29, vcc, 0, v27, vcc
	v_add_co_u32_e32 v126, vcc, 0x3000, v26
	s_nop 1
	v_addc_co_u32_e32 v127, vcc, 0, v27, vcc
	global_load_dwordx2 v[20:21], v[28:29], off offset:-4096
	global_load_dwordx2 v[22:23], v[28:29], off offset:-3072
	global_load_dwordx4 v[112:115], v[24:25], off offset:64
	global_load_dwordx2 v[116:117], v[126:127], off offset:-4096
	global_load_dwordx2 v[118:119], v[126:127], off offset:-3072
	global_load_dwordx4 v[120:123], v[24:25], off offset:96
	global_load_dwordx2 v[124:125], v[126:127], off
	global_load_dwordx2 v[126:127], v[126:127], off offset:1024
	s_waitcnt vmcnt(9)
	v_mfma_f32_32x32x16_bf16 v[0:15], v[0:3], v[4:7], 0
	s_waitcnt vmcnt(6)
	v_mfma_f32_32x32x16_bf16 v[0:15], v[16:19], v[20:23], v[0:15]
	s_waitcnt vmcnt(3)
	v_mfma_f32_32x32x16_bf16 v[0:15], v[112:115], v[116:119], v[0:15]
	s_waitcnt vmcnt(0)
	v_mfma_f32_32x32x16_bf16 v[0:15], v[120:123], v[124:127], v[0:15]
	s_and_b64 vcc, exec, s[8:9]
	s_cbranch_vccnz .LBB0_464
	v_mov_b32_e32 v16, 0
	s_andn2_b64 vcc, exec, s[44:45]
	v_mov_b32_e32 v17, 0
	v_mov_b32_e32 v18, 0
	v_mov_b32_e32 v19, 0
	v_mov_b32_e32 v20, 0
	v_mov_b32_e32 v21, 0
	v_mov_b32_e32 v22, 0
	v_mov_b32_e32 v23, 0
	v_mov_b32_e32 v24, 0
	v_mov_b32_e32 v25, 0
	v_mov_b32_e32 v26, 0
	v_mov_b32_e32 v27, 0
	v_mov_b32_e32 v28, 0
	v_mov_b32_e32 v29, 0
	v_mov_b32_e32 v30, 0
	v_mov_b32_e32 v31, 0
	s_cbranch_vccnz .LBB0_463
	s_lshl_b64 s[8:9], s[56:57], 8
	s_lshl_b32 s12, s3, 6
	s_lshl_b64 s[8:9], s[8:9], 1
	v_readlane_b32 s16, v252, 0
	s_add_u32 s8, s16, s8
	v_readlane_b32 s16, v252, 1
	s_addc_u32 s9, s16, s9
	s_lshl_b32 s12, s12, 1
	s_add_u32 s8, s8, s12
	v_lshl_add_u64 v[16:17], s[6:7], 0, v[66:67]
	s_addc_u32 s9, s9, 0
	v_lshl_add_u64 v[44:45], v[16:17], 0, v[32:33]
	v_lshlrev_b32_e32 v16, 1, v62
	v_mov_b32_e32 v17, v33
	v_lshl_add_u64 v[16:17], s[8:9], 0, v[16:17]
	v_lshl_add_u64 v[46:47], v[16:17], 0, v[32:33]
	global_load_dwordx4 v[16:19], v[44:45], off
	global_load_dwordx4 v[20:23], v[46:47], off
	global_load_dwordx4 v[36:39], v[44:45], off offset:32
	global_load_dwordx4 v[40:43], v[46:47], off offset:32
	global_load_dwordx4 v[112:115], v[44:45], off offset:64
	global_load_dwordx4 v[116:119], v[46:47], off offset:64
	global_load_dwordx4 v[120:123], v[44:45], off offset:96
	global_load_dwordx4 v[124:127], v[46:47], off offset:96
	s_waitcnt vmcnt(6)
	v_mfma_f32_32x32x16_bf16 v[16:31], v[16:19], v[20:23], 0
	s_waitcnt vmcnt(4)
	v_mfma_f32_32x32x16_bf16 v[16:31], v[36:39], v[40:43], v[16:31]
	s_waitcnt vmcnt(2)
	v_mfma_f32_32x32x16_bf16 v[16:31], v[112:115], v[116:119], v[16:31]
	s_waitcnt vmcnt(0)
	v_mfma_f32_32x32x16_bf16 v[16:31], v[120:123], v[124:127], v[16:31]
	s_branch .LBB0_463

; DI float bf2f(bf16_t v) { return __uint_as_float((unsigned)v << 16); }
; DI bf16_t f2bf(float f) { return (bf16_t)cvt_pk_bf16(f, 0.f); }
; DI void prep_phase(PARAMS P, int l, int g, LAS unsigned char* lds, int wave, int lane) {
;     ...
;             for (int t0 = tb; t0 < tb + 32; t0 += 8) {
;                 float qv[8], kv[8];
; #pragma unroll
;                 for (int j = 0; j < 8; ++j) { const size_t o = (size_t)(row0 + t0 + j) * 256 + c; qv[j] = bf2f(gq[o]); kv[j] = bf2f(gk[o]); }
; #pragma unroll
;                 for (int j = 0; j < 8; ++j) { const int t = t0 + j; const float bt = Bl[t * 256 + c] + boff; const size_t o = (size_t)(row0 + t) * 256 + c;
;                     gq[o] = f2bf(qv[j] * __expf(bt)); gk[o] = f2bf(kv[j] * __expf(-bt)); ks[o] = f2bf(t < L ? kv[j] * __expf(bl - bt) : 0.f); }
.LBB0_726:
	s_or_b64 exec, exec, s[4:5]
	v_cndmask_b32_e64 v9, v0, 0, s[42:43]
	v_add_u32_e32 v0, s6, v90
	v_ashrrev_i32_e32 v1, 31, v0
	v_lshlrev_b64 v[0:1], 9, v[0:1]
	v_lshl_add_u64 v[0:1], v[82:83], 0, v[0:1]
	s_mov_b64 s[4:5], 0
	v_mov_b32_e32 v10, v120
	v_mov_b32_e32 v11, v90
	s_waitcnt vmcnt(0)
.LBB0_727:
	v_add_co_u32_e32 v2, vcc, 0xfb140000, v0
	s_nop 1
	v_addc_co_u32_e32 v3, vcc, -1, v1, vcc
	v_add_co_u32_e32 v4, vcc, 0xfb5a0000, v0
	s_nop 1
	v_addc_co_u32_e32 v5, vcc, -1, v1, vcc
	global_load_ushort v23, v[2:3], off offset:-3584
	global_load_ushort v24, v[4:5], off offset:-3584
	global_load_ushort v25, v[2:3], off offset:-3072
	global_load_ushort v26, v[4:5], off offset:-3072
	global_load_ushort v27, v[2:3], off offset:-2560
	global_load_ushort v22, v[4:5], off offset:-2560
	global_load_ushort v21, v[2:3], off offset:-2048
	global_load_ushort v20, v[4:5], off offset:-2048
	global_load_ushort v19, v[2:3], off offset:-1536
	global_load_ushort v18, v[4:5], off offset:-1536
	global_load_ushort v17, v[2:3], off offset:-1024
	global_load_ushort v16, v[4:5], off offset:-1024
	global_load_ushort v15, v[2:3], off offset:-512
	global_load_ushort v14, v[4:5], off offset:-512
	global_load_ushort v13, v[2:3], off
	global_load_ushort v12, v[4:5], off
	v_cmp_gt_i32_e32 vcc, s7, v11
	s_waitcnt vmcnt(0)
	v_lshlrev_b32_e32 v23, 16, v23
	v_lshlrev_b32_e32 v24, 16, v24
	v_lshlrev_b32_e32 v25, 16, v25
	v_lshlrev_b32_e32 v26, 16, v26
	v_lshlrev_b32_e32 v27, 16, v27
	v_lshlrev_b32_e32 v22, 16, v22
	v_lshlrev_b32_e32 v21, 16, v21
	v_lshlrev_b32_e32 v20, 16, v20
	v_lshlrev_b32_e32 v19, 16, v19
	v_lshlrev_b32_e32 v18, 16, v18
	v_lshlrev_b32_e32 v17, 16, v17
	v_lshlrev_b32_e32 v16, 16, v16
	v_lshlrev_b32_e32 v15, 16, v15
	v_lshlrev_b32_e32 v14, 16, v14
	v_lshlrev_b32_e32 v13, 16, v13
	v_lshlrev_b32_e32 v12, 16, v12
	ds_read2st64_b32 v[6:7], v10 offset1:4
	s_waitcnt lgkmcnt(0)
	v_add_f32_e32 v6, v9, v6
	v_mul_f32_e32 v28, 0x3fb8aa3b, v6
	v_exp_f32_e32 v28, v28
	v_add_f32_e32 v7, v9, v7
	v_mul_f32_e32 v23, v28, v23
	v_cvt_pk_bf16_f32 v23, v23, s0
	global_store_short v[2:3], v23, off offset:-3584
	v_mul_f32_e32 v23, 0xbfb8aa3b, v6
	v_sub_f32_e32 v6, v8, v6
	v_mul_f32_e32 v6, 0x3fb8aa3b, v6
	v_exp_f32_e32 v6, v6
	v_exp_f32_e32 v23, v23
	v_mul_f32_e32 v6, v6, v24
	v_cvt_pk_bf16_f32 v6, v6, s0
	v_cndmask_b32_e32 v6, 0, v6, vcc
	global_store_short v[0:1], v6, off offset:-3584
	v_add_u32_e32 v6, 1, v11
	v_mul_f32_e32 v23, v23, v24
	v_cmp_gt_i32_e32 vcc, s7, v6
	v_sub_f32_e32 v6, v8, v7
	v_cvt_pk_bf16_f32 v23, v23, s0
	v_mul_f32_e32 v6, 0x3fb8aa3b, v6
	global_store_short v[4:5], v23, off offset:-3584
	v_mul_f32_e32 v23, 0x3fb8aa3b, v7
	v_exp_f32_e32 v6, v6
	v_exp_f32_e32 v23, v23
	v_mul_f32_e32 v6, v6, v26
	v_mul_f32_e32 v23, v23, v25
	v_cvt_pk_bf16_f32 v6, v6, s0
	v_cvt_pk_bf16_f32 v23, v23, s0
	v_cndmask_b32_e32 v6, 0, v6, vcc
	global_store_short v[2:3], v23, off offset:-3072
	v_mul_f32_e32 v23, 0xbfb8aa3b, v7
	global_store_short v[0:1], v6, off offset:-3072
	ds_read2st64_b32 v[6:7], v10 offset0:8 offset1:12
	v_exp_f32_e32 v23, v23
	s_waitcnt lgkmcnt(0)
; DI bf16_t f2bf(float f) { return (bf16_t)cvt_pk_bf16(f, 0.f); }
; DI void prep_phase(PARAMS P, int l, int g, LAS unsigned char* lds, int wave, int lane) {
;     ...
; #pragma unroll
;                 for (int j = 0; j < 8; ++j) { const int t = t0 + j; const float bt = Bl[t * 256 + c] + boff; const size_t o = (size_t)(row0 + t) * 256 + c;
;                     gq[o] = f2bf(qv[j] * __expf(bt)); gk[o] = f2bf(kv[j] * __expf(-bt)); ks[o] = f2bf(t < L ? kv[j] * __expf(bl - bt) : 0.f); }
;             }
	v_add_f32_e32 v6, v9, v6
	v_mul_f32_e32 v24, 0x3fb8aa3b, v6
	v_exp_f32_e32 v24, v24
	v_mul_f32_e32 v23, v23, v26
	v_cvt_pk_bf16_f32 v23, v23, s0
	global_store_short v[4:5], v23, off offset:-3072
	v_mul_f32_e32 v24, v24, v27
	v_cvt_pk_bf16_f32 v24, v24, s0
	global_store_short v[2:3], v24, off offset:-2560
	v_mul_f32_e32 v24, 0xbfb8aa3b, v6
	v_sub_f32_e32 v6, v8, v6
	v_mul_f32_e32 v6, 0x3fb8aa3b, v6
	v_exp_f32_e32 v6, v6
	v_add_u32_e32 v23, 2, v11
	v_exp_f32_e32 v24, v24
	v_cmp_gt_i32_e32 vcc, s7, v23
	v_mul_f32_e32 v6, v6, v22
	v_cvt_pk_bf16_f32 v6, v6, s0
	v_cndmask_b32_e32 v6, 0, v6, vcc
	global_store_short v[0:1], v6, off offset:-2560
	v_add_u32_e32 v6, 3, v11
	v_add_f32_e32 v7, v9, v7
	v_cmp_gt_i32_e32 vcc, s7, v6
	v_sub_f32_e32 v6, v8, v7
	v_mul_f32_e32 v24, v24, v22
	v_mul_f32_e32 v22, 0x3fb8aa3b, v7
	v_mul_f32_e32 v6, 0x3fb8aa3b, v6
	v_exp_f32_e32 v22, v22
	v_exp_f32_e32 v6, v6
	v_cvt_pk_bf16_f32 v24, v24, s0
	global_store_short v[4:5], v24, off offset:-2560
	v_mul_f32_e32 v21, v22, v21
	v_mul_f32_e32 v6, v6, v20
	v_cvt_pk_bf16_f32 v21, v21, s0
	v_cvt_pk_bf16_f32 v6, v6, s0
	global_store_short v[2:3], v21, off offset:-2048
	v_mul_f32_e32 v21, 0xbfb8aa3b, v7
	v_cndmask_b32_e32 v6, 0, v6, vcc
	v_exp_f32_e32 v21, v21
	global_store_short v[0:1], v6, off offset:-2048
	ds_read2st64_b32 v[6:7], v10 offset0:16 offset1:20
	v_mul_f32_e32 v21, v21, v20
	v_cvt_pk_bf16_f32 v21, v21, s0
	global_store_short v[4:5], v21, off offset:-2048
	s_waitcnt lgkmcnt(0)
	v_add_f32_e32 v6, v9, v6
	v_mul_f32_e32 v21, 0x3fb8aa3b, v6
	v_exp_f32_e32 v21, v21
	v_add_u32_e32 v20, 4, v11
	v_cmp_gt_i32_e32 vcc, s7, v20
	v_add_f32_e32 v7, v9, v7
	v_mul_f32_e32 v19, v21, v19
	v_cvt_pk_bf16_f32 v19, v19, s0
	global_store_short v[2:3], v19, off offset:-1536
	v_mul_f32_e32 v19, 0xbfb8aa3b, v6
	v_sub_f32_e32 v6, v8, v6
	v_mul_f32_e32 v6, 0x3fb8aa3b, v6
	v_exp_f32_e32 v6, v6
	v_exp_f32_e32 v19, v19
	v_mul_f32_e32 v6, v6, v18
	v_cvt_pk_bf16_f32 v6, v6, s0
	v_cndmask_b32_e32 v6, 0, v6, vcc
	global_store_short v[0:1], v6, off offset:-1536
	v_add_u32_e32 v6, 5, v11
	v_cmp_gt_i32_e32 vcc, s7, v6
	v_sub_f32_e32 v6, v8, v7
	v_mul_f32_e32 v19, v19, v18
	v_mul_f32_e32 v18, 0x3fb8aa3b, v7
	v_mul_f32_e32 v6, 0x3fb8aa3b, v6
	v_exp_f32_e32 v18, v18
	v_exp_f32_e32 v6, v6
	v_cvt_pk_bf16_f32 v19, v19, s0
	global_store_short v[4:5], v19, off offset:-1536
	v_mul_f32_e32 v17, v18, v17
	v_mul_f32_e32 v6, v6, v16
	v_cvt_pk_bf16_f32 v17, v17, s0
	v_cvt_pk_bf16_f32 v6, v6, s0
	global_store_short v[2:3], v17, off offset:-1024
	v_mul_f32_e32 v17, 0xbfb8aa3b, v7
	v_cndmask_b32_e32 v6, 0, v6, vcc
	v_exp_f32_e32 v17, v17
	global_store_short v[0:1], v6, off offset:-1024
	ds_read2st64_b32 v[6:7], v10 offset0:24 offset1:28
	v_add_u32_e32 v10, 0x2000, v10
	v_mul_f32_e32 v17, v17, v16
	v_cvt_pk_bf16_f32 v17, v17, s0
	global_store_short v[4:5], v17, off offset:-1024
	s_waitcnt lgkmcnt(0)
	v_add_f32_e32 v6, v9, v6
	v_mul_f32_e32 v17, 0x3fb8aa3b, v6
	v_exp_f32_e32 v17, v17
	v_add_f32_e32 v7, v9, v7
	v_add_u32_e32 v16, 6, v11
	v_cmp_gt_i32_e32 vcc, s7, v16
	v_mul_f32_e32 v15, v17, v15
	v_cvt_pk_bf16_f32 v15, v15, s0
	global_store_short v[2:3], v15, off offset:-512
	v_mul_f32_e32 v15, 0xbfb8aa3b, v6
	v_sub_f32_e32 v6, v8, v6
	v_mul_f32_e32 v6, 0x3fb8aa3b, v6
	v_exp_f32_e32 v15, v15
	v_exp_f32_e32 v6, v6
	v_mul_f32_e32 v15, v15, v14
	v_mul_f32_e32 v6, v6, v14
	v_mul_f32_e32 v14, 0x3fb8aa3b, v7
	v_exp_f32_e32 v14, v14
	v_cvt_pk_bf16_f32 v6, v6, s0
	v_cndmask_b32_e32 v6, 0, v6, vcc
	global_store_short v[0:1], v6, off offset:-512
	v_mul_f32_e32 v13, v14, v13
	v_cvt_pk_bf16_f32 v13, v13, s0
	global_store_short v[2:3], v13, off
	v_mul_f32_e32 v2, 0xbfb8aa3b, v7
	v_exp_f32_e32 v2, v2
	v_add_u32_e32 v6, 7, v11
	v_cmp_gt_i32_e32 vcc, s7, v6
	v_add_u32_e32 v11, 8, v11
	v_mul_f32_e32 v2, v2, v12
	v_cvt_pk_bf16_f32 v2, v2, s0
	global_store_short v[4:5], v2, off
	v_sub_f32_e32 v2, v8, v7
	v_mul_f32_e32 v2, 0x3fb8aa3b, v2
	v_exp_f32_e32 v2, v2
	v_cvt_pk_bf16_f32 v15, v15, s0
	global_store_short v[4:5], v15, off offset:-512
	v_mul_f32_e32 v2, v2, v12
	v_cvt_pk_bf16_f32 v2, v2, s0
	v_cndmask_b32_e32 v2, 0, v2, vcc
	v_cmp_ge_i32_e32 vcc, v11, v39
	global_store_short v[0:1], v2, off
	v_lshl_add_u64 v[0:1], v[0:1], 0, s[84:85]
	s_or_b64 s[4:5], vcc, s[4:5]
	s_andn2_b64 exec, exec, s[4:5]
	s_cbranch_execnz .LBB0_727
	s_or_b64 exec, exec, s[4:5]

; #define LAS __attribute__((address_space(3)))
; #define MFMA32(a, b, c) __builtin_amdgcn_mfma_f32_32x32x16_bf16((a), (b), (c), 0, 0, 0)
; DI void prep_phase(PARAMS P, int l, int g, LAS unsigned char* lds, int wave, int lane) {
;     ...
;             for (int cbk = wave * 6; cbk < wave * 6 + 6; ++cbk) {
;                 const int mt = cbk >> 4, hd = (cbk >> 2) & 3, nb = cbk & 3;
;                 const bf16_t* wt = wm + (size_t)(mt * 4 + hd) * 16384 + (size_t)(32 * nb + r) * 128 + 8 * hh;
;                 const LAS bf16_t* al = (mt == 2 ? Xl : Cl) + r * 520 + hd * 128 + 8 * hh;
;                 f32x16 a0, a1;
; #pragma unroll
;                 for (int i = 0; i < 16; ++i) { a0[i] = 0.f; a1[i] = 0.f; }
; #pragma unroll
;                 for (int ks = 0; ks < 8; ++ks) {
;                     const bf16x8 b = *(const bf16x8*)(wt + 16 * ks);
;                     const bf16x8 x0 = *(const LAS bf16x8*)(al + 16 * ks), x1 = *(const LAS bf16x8*)(al + 32 * 520 + 16 * ks);
;                     a0 = MFMA32(x0, b, a0); a1 = MFMA32(x1, b, a1);
;                 }
.LBB0_746:
	s_add_i32 s33, s60, s7
	s_ashr_i32 s64, s33, 4
	s_bfe_u32 s17, s33, 0x20002
	s_lshl_b32 s4, s64, 2
	s_or_b32 s4, s4, s17
	s_ashr_i32 s5, s4, 31
	s_lshl_b64 s[4:5], s[4:5], 15
	s_add_u32 s4, s19, s4
	s_addc_u32 s5, s35, s5
	s_and_b32 s20, s16, 0x60
	v_or_b32_e32 v125, s20, v35
	v_lshlrev_b32_e32 v32, 8, v125
	s_waitcnt lgkmcnt(0)
	v_lshl_add_u64 v[0:1], s[4:5], 0, v[32:33]
	v_mov_b32_e32 v87, v33
	v_lshl_add_u64 v[88:89], v[0:1], 0, v[86:87]
	global_load_dwordx4 v[16:19], v[88:89], off
	global_load_dwordx4 v[130:133], v[88:89], off offset:32
	global_load_dwordx4 v[140:143], v[88:89], off offset:64
	global_load_dwordx4 v[144:147], v[88:89], off offset:96
	global_load_dwordx4 v[148:151], v[88:89], off offset:128
	global_load_dwordx4 v[152:155], v[88:89], off offset:160
	global_load_dwordx4 v[156:159], v[88:89], off offset:192
	global_load_dwordx4 v[160:163], v[88:89], off offset:224
	s_cmp_eq_u32 s64, 2
	s_cselect_b32 s4, s27, 0
	s_lshl_b32 s21, s17, 8
	s_add_i32 s4, s21, s4
	v_add3_u32 v32, s4, v93, v86
	ds_read_b128 v[20:23], v32 offset:33280
	ds_read_b128 v[0:3], v32
	ds_read_b128 v[126:129], v32 offset:32
	ds_read_b128 v[134:137], v32 offset:33312
	s_mov_b64 s[4:5], -1
	s_cmp_lg_u32 s64, 1
	s_waitcnt vmcnt(7) lgkmcnt(2)
	v_mfma_f32_32x32x16_bf16 v[0:15], v[0:3], v[16:19], 0
	s_waitcnt vmcnt(6) lgkmcnt(1)
	v_mfma_f32_32x32x16_bf16 v[0:15], v[126:129], v[130:133], v[0:15]
	v_mfma_f32_32x32x16_bf16 v[16:31], v[20:23], v[16:19], 0
	s_waitcnt lgkmcnt(0)
	v_mfma_f32_32x32x16_bf16 v[16:31], v[134:137], v[130:133], v[16:31]
	ds_read_b128 v[130:133], v32 offset:64
	ds_read_b128 v[134:137], v32 offset:33344
	s_waitcnt vmcnt(5) lgkmcnt(1)
	v_mfma_f32_32x32x16_bf16 v[0:15], v[130:133], v[140:143], v[0:15]
	s_waitcnt lgkmcnt(0)
	v_mfma_f32_32x32x16_bf16 v[16:31], v[134:137], v[140:143], v[16:31]
	ds_read_b128 v[130:133], v32 offset:96
	ds_read_b128 v[134:137], v32 offset:33376
	s_waitcnt vmcnt(4) lgkmcnt(1)
	v_mfma_f32_32x32x16_bf16 v[0:15], v[130:133], v[144:147], v[0:15]
	s_waitcnt lgkmcnt(0)
	v_mfma_f32_32x32x16_bf16 v[16:31], v[134:137], v[144:147], v[16:31]
	ds_read_b128 v[130:133], v32 offset:128
	ds_read_b128 v[134:137], v32 offset:33408
	s_waitcnt vmcnt(3) lgkmcnt(1)
	v_mfma_f32_32x32x16_bf16 v[0:15], v[130:133], v[148:151], v[0:15]
	s_waitcnt lgkmcnt(0)
	v_mfma_f32_32x32x16_bf16 v[16:31], v[134:137], v[148:151], v[16:31]
	ds_read_b128 v[130:133], v32 offset:160
	ds_read_b128 v[134:137], v32 offset:33440
	s_waitcnt vmcnt(2) lgkmcnt(1)
	v_mfma_f32_32x32x16_bf16 v[0:15], v[130:133], v[152:155], v[0:15]
	s_waitcnt lgkmcnt(0)
	v_mfma_f32_32x32x16_bf16 v[16:31], v[134:137], v[152:155], v[16:31]
	ds_read_b128 v[130:133], v32 offset:192
	ds_read_b128 v[134:137], v32 offset:33472
	s_waitcnt vmcnt(1) lgkmcnt(1)
	v_mfma_f32_32x32x16_bf16 v[0:15], v[130:133], v[156:159], v[0:15]
	s_waitcnt lgkmcnt(0)
	v_mfma_f32_32x32x16_bf16 v[16:31], v[134:137], v[156:159], v[16:31]
	ds_read_b128 v[130:133], v32 offset:224
	ds_read_b128 v[134:137], v32 offset:33504
	v_lshl_or_b32 v32, s17, 7, v125
	v_lshlrev_b32_e32 v32, 1, v32
	s_waitcnt vmcnt(0) lgkmcnt(1)
	v_mfma_f32_32x32x16_bf16 v[0:15], v[130:133], v[160:163], v[0:15]
	s_waitcnt lgkmcnt(0)
	v_mfma_f32_32x32x16_bf16 v[16:31], v[134:137], v[160:163], v[16:31]
	s_cbranch_scc1 .LBB0_748
	s_andn2_b64 vcc, exec, s[4:5]
	s_cbranch_vccnz .LBB0_745
	s_branch .LBB0_749
